# mLSTM: Q/K staging via global_load_lds (direct to LDS) issued after barrier 3; VGPR loads kept as L2 warmers
# baseline (speedup 1.0000x reference)
.LBB0_659:
	s_or_b64 exec, exec, s[4:5]
	s_lshr_b32 s4, s92, 3
	s_and_b32 s59, s4, 3
	s_lshl_b32 s97, s94, 6
	s_cmp_gt_i32 s55, 3
	s_cselect_b64 s[68:69], -1, 0
	s_add_i32 s4, s55, -4
	s_lshr_b32 s6, s4, 1
	v_and_b32_e32 v99, 48, v83
	v_bfe_u32 v222, v83, 5, 1
	v_lshlrev_b32_e32 v222, 4, v222
	v_bfe_u32 v223, v83, 4, 1
	v_lshl_or_b32 v222, v223, 8, v222
	v_bfe_u32 v223, v83, 5, 1
	v_mul_u32_u24_e32 v223, 0xf0, v223
	v_lshrrev_b32_e32 v226, 1, v83
	v_and_b32_e32 v226, 0xffffffe0, v226
	v_sub_u32_e32 v223, v223, v226
	v_bfe_u32 v224, v83, 2, 3
	v_lshlrev_b32_e32 v224, 5, v224
	v_bfe_u32 v227, v83, 1, 1
	v_lshl_or_b32 v224, v227, 4, v224
	v_and_b32_e32 v228, 1, v83
	v_lshl_or_b32 v224, v228, 8, v224
	v_lshlrev_b32_e32 v225, 8, v227
	v_lshl_or_b32 v225, v228, 3, v225
	v_add_u32_e32 v225, v225, v226
	s_lshl_b32 s4, s55, 4
	v_lshl_add_u32 v103, s6, 7, v222
	s_lshl_b32 s6, s6, 5
	v_lshlrev_b32_e32 v66, 2, v84
	s_and_b32 s17, s4, 16
	s_add_i32 s6, s6, 64
	s_ashr_i32 s70, s12, 7
	s_bfe_u32 s71, s12, 0x10006
	v_lshl_add_u32 v21, v24, 4, 0
	v_add_u32_e32 v106, 0, v66
	v_or_b32_e32 v88, s17, v84
	v_mul_u32_u24_e32 v24, 0x20c, v84
	s_mov_b32 s4, 0xc000
	s_cmp_lg_u32 s70, 1
	v_add3_u32 v105, v106, v24, s4
	v_or_b32_e32 v24, s6, v88
	s_cselect_b64 s[6:7], -1, 0
	s_bitcmp1_b32 s12, 6
	s_cselect_b64 s[8:9], -1, 0
	s_or_b64 s[64:65], s[6:7], s[8:9]
	s_lshl_b32 s6, s70, 4
	v_lshlrev_b32_e32 v102, 2, v24
	v_or_b32_e32 v24, s6, v84
	v_mul_lo_u32 v24, v24, s83
	v_lshlrev_b32_e32 v68, 2, v23
	v_add_u32_e32 v101, 0, v24
	v_or_b32_e32 v98, s6, v68
	s_and_b32 s6, s12, 0xffffff80
	v_lshrrev_b32_e32 v24, 2, v84
	s_add_i32 s86, s35, s6
	v_or_b32_e32 v24, v26, v24
	s_ashr_i32 s6, s12, 3
	s_lshl_b32 s16, s58, 9
	v_mad_u32_u24 v28, v24, s83, 0
	v_lshlrev_b32_e32 v24, 3, v83
	s_and_b32 s56, s6, -16
	s_add_i32 s42, s42, s16
	v_and_or_b32 v29, v24, 24, s13
	v_or_b32_e32 v24, s56, v84
	s_and_b32 s16, s42, 0xfffff800
	v_mul_lo_u32 v26, v24, s82
	s_or_b32 s17, s16, s17
	v_add_u32_e32 v70, 0, v26
	s_movk_i32 s6, 0x1c0
	v_or_b32_e32 v109, s17, v84
	s_lshl_b32 s17, s70, 6
	v_cmp_gt_u32_e64 s[4:5], 16, v27
	v_lshl_or_b32 v96, s71, 4, v84
	v_mad_u64_u32 v[26:27], s[6:7], v24, s6, v[70:71]
	v_or_b32_e32 v24, 2, v98
	s_add_i32 s17, s17, 0x18500
	v_cmp_gt_i32_e64 s[10:11], v24, v96
	v_or_b32_e32 v24, 3, v98
	v_lshl_or_b32 v111, v23, 4, s17
	v_mul_hi_u32_u24_e32 v23, 0x7000, v84
	s_mul_hi_i32 s42, s16, 0x3800
	v_mul_lo_u32 v108, v25, s87
	v_cmp_gt_i32_e64 s[6:7], v24, v96
	v_mul_u32_u24_e32 v24, 0x7000, v84
	s_mul_i32 s58, s16, 0x3800
	v_or_b32_e32 v25, s42, v23
	s_lshl_b32 s42, s92, 4
	v_or_b32_e32 v23, s58, v24
	s_and_b32 s42, s42, 0x600
	s_mul_i32 s100, s16, 0x3800
	s_mul_hi_u32 s101, s16, 0x3800
	s_add_u32 s100, s100, s28
	s_addc_u32 s101, s101, s29
	s_add_u32 s100, s100, s42
	s_addc_u32 s101, s101, 0
	s_add_u32 s100, s100, 0x2000
	s_addc_u32 s101, s101, 0
	v_or_b32_e32 v23, s42, v23
	s_ashr_i32 s17, s16, 31
	v_lshl_or_b32 v24, s59, 7, v23
	v_mul_lo_u32 v27, v16, s83
	v_lshl_add_u64 v[18:19], v[18:19], 1, v[24:25]
	v_lshl_add_u64 v[16:17], v[16:17], 0, s[16:17]
	s_waitcnt lgkmcnt(0)
	s_barrier
; #define LAS __attribute__((address_space(3)))
; __device__ __forceinline__ void mlstm_item(const Args& a, LAS unsigned char* L, bool sample, int b, int hh, int sl, bool dry = false) {
;     ...
;         for (int i = 0; i < 2; ++i) { *(LAS u32x4*)(L + L_QS + (prow + 16 * i) * 528 + pcc * 16) = qreg[i]; *(LAS u32x4*)(L + L_KS + (prow + 16 * i) * 528 + pcc * 16) = kreg[i]; }
	v_mad_u32_u24 v104, v88, s83, 0
	v_lshl_add_u64 v[72:73], s[28:29], 0, v[18:19]
	v_mad_u64_u32 v[18:19], s[16:17], v16, s84, 0
	v_mul_u32_u24_e32 v20, 0x210, v84
	v_lshlrev_b32_e32 v107, 3, v84
	v_mad_u32_u24 v100, v96, s83, 0
	v_add_u32_e32 v30, 0, v99
	v_mad_i32_i24 v31, v88, s33, v104
	v_mul_u32_u24_e32 v32, 0x50, v84
	v_mad_i32_i24 v17, v17, s84, v19
	v_or3_b32 v16, v18, s42, v60
	v_mov_b32_e32 v36, 0
	v_cmp_gt_i32_e64 s[14:15], 16, v83
	v_mad_i32_i24 v93, v96, s33, v100
	v_lshlrev_b32_e32 v94, 1, v98
	v_lshlrev_b32_e32 v92, 2, v96
	v_lshl_add_u32 v89, v88, 2, s35
	s_ashr_i32 s57, s56, 31
	v_cmp_gt_i32_e64 s[12:13], v98, v96
	v_cmp_lt_i32_e64 s[8:9], v98, v96
	v_lshl_or_b32 v110, s71, 6, v66
	v_lshl_add_u64 v[74:75], s[28:29], 0, v[16:17]
	s_mov_b32 s16, 0
	s_mov_b64 s[70:71], 0
	s_lshl_b32 s58, s97, 1
	v_lshlrev_b32_e32 v60, 1, v68
	v_add_u32_e32 v112, v224, v27
	v_add_u32_e32 v97, v28, v225
	v_add_u32_e32 v95, v30, v32
	v_add_u32_e32 v91, v31, v99
	v_add_u32_e32 v90, v26, v222
	v_add_u32_e32 v113, v22, v20
	v_add_u32_e32 v113, v113, v223
	v_add_u32_e32 v86, v86, v223
	v_add_u32_e32 v85, v85, v223
	v_add_u32_e32 v67, v67, v223
	v_mov_b32_e32 v114, v107
	v_mov_b32_e32 v37, v36
	v_mov_b32_e32 v38, v36
	v_mov_b32_e32 v39, v36
	v_mov_b32_e32 v52, v36
	v_mov_b32_e32 v53, v36
	v_mov_b32_e32 v54, v36
	v_mov_b32_e32 v55, v36
	v_mov_b32_e32 v48, v36
	v_mov_b32_e32 v49, v36
	v_mov_b32_e32 v50, v36
	v_mov_b32_e32 v51, v36
	v_mov_b32_e32 v44, v36
	v_mov_b32_e32 v45, v36
	v_mov_b32_e32 v46, v36
	v_mov_b32_e32 v47, v36
	v_mov_b32_e32 v40, v36
	v_mov_b32_e32 v41, v36
	v_mov_b32_e32 v42, v36
	v_mov_b32_e32 v43, v36
	v_mov_b32_e32 v32, v36
	v_mov_b32_e32 v33, v36
	v_mov_b32_e32 v34, v36
	v_mov_b32_e32 v35, v36
	v_mov_b32_e32 v28, v36
	v_mov_b32_e32 v29, v36
	v_mov_b32_e32 v30, v36
	v_mov_b32_e32 v31, v36
	v_mov_b32_e32 v24, v36
	v_mov_b32_e32 v25, v36
	v_mov_b32_e32 v26, v36
	v_mov_b32_e32 v27, v36
	v_mov_b32_e32 v20, v36
	v_mov_b32_e32 v21, v36
	v_mov_b32_e32 v22, v36
	v_mov_b32_e32 v23, v36
	v_mov_b32_e32 v16, v36
	v_mov_b32_e32 v17, v36
	v_mov_b32_e32 v18, v36
	v_mov_b32_e32 v19, v36
	v_mov_b32_e32 v234, v83
	v_mul_u32_u24_e32 v235, 0x7c2, v234
	v_lshrrev_b32_e32 v235, 16, v235
	v_mul_u32_u24_e32 v236, 33, v235
	v_sub_u32_e32 v236, v234, v236
	v_and_b32_e32 v237, 15, v236
	v_lshrrev_b32_e32 v238, 1, v237
	v_lshlrev_b32_e32 v238, 6, v238
	v_and_b32_e32 v237, 1, v237
	v_lshl_or_b32 v238, v237, 5, v238
	v_lshrrev_b32_e32 v237, 4, v236
	v_lshl_or_b32 v238, v237, 4, v238
	v_lshrrev_b32_e32 v237, 5, v235
	v_lshl_or_b32 v238, v237, 11, v238
	v_and_b32_e32 v237, 31, v235
	v_mul_u32_u24_e32 v237, 0x3800, v237
	v_add_u32_e32 v229, v237, v238
	v_add_u32_e32 v234, 512, v83
	v_mul_u32_u24_e32 v235, 0x7c2, v234
	v_lshrrev_b32_e32 v235, 16, v235
	v_mul_u32_u24_e32 v236, 33, v235
	v_sub_u32_e32 v236, v234, v236
	v_and_b32_e32 v237, 15, v236
	v_lshrrev_b32_e32 v238, 1, v237
	v_lshlrev_b32_e32 v238, 6, v238
	v_and_b32_e32 v237, 1, v237
	v_lshl_or_b32 v238, v237, 5, v238
	v_lshrrev_b32_e32 v237, 4, v236
	v_lshl_or_b32 v238, v237, 4, v238
	v_lshrrev_b32_e32 v237, 5, v235
	v_lshl_or_b32 v238, v237, 11, v238
	v_and_b32_e32 v237, 31, v235
	v_mul_u32_u24_e32 v237, 0x3800, v237
	v_add_u32_e32 v230, v237, v238
	v_add_u32_e32 v234, 1024, v83
	v_mul_u32_u24_e32 v235, 0x7c2, v234
	v_lshrrev_b32_e32 v235, 16, v235
	v_mul_u32_u24_e32 v236, 33, v235
	v_sub_u32_e32 v236, v234, v236
	v_and_b32_e32 v237, 15, v236
	v_lshrrev_b32_e32 v238, 1, v237
	v_lshlrev_b32_e32 v238, 6, v238
	v_and_b32_e32 v237, 1, v237
	v_lshl_or_b32 v238, v237, 5, v238
	v_lshrrev_b32_e32 v237, 4, v236
	v_lshl_or_b32 v238, v237, 4, v238
	v_lshrrev_b32_e32 v237, 5, v235
	v_lshl_or_b32 v238, v237, 11, v238
	v_and_b32_e32 v237, 31, v235
	v_mul_u32_u24_e32 v237, 0x3800, v237
	v_add_u32_e32 v231, v237, v238
	v_add_u32_e32 v234, 1536, v83
	v_mul_u32_u24_e32 v235, 0x7c2, v234
	v_lshrrev_b32_e32 v235, 16, v235
	v_mul_u32_u24_e32 v236, 33, v235
	v_sub_u32_e32 v236, v234, v236
	v_and_b32_e32 v237, 15, v236
	v_lshrrev_b32_e32 v238, 1, v237
	v_lshlrev_b32_e32 v238, 6, v238
	v_and_b32_e32 v237, 1, v237
	v_lshl_or_b32 v238, v237, 5, v238
	v_lshrrev_b32_e32 v237, 4, v236
	v_lshl_or_b32 v238, v237, 4, v238
	v_lshrrev_b32_e32 v237, 5, v235
	v_lshl_or_b32 v238, v237, 11, v238
	v_and_b32_e32 v237, 31, v235
	v_mul_u32_u24_e32 v237, 0x3800, v237
	v_add_u32_e32 v232, v237, v238
	v_add_u32_e32 v234, 2048, v83
	v_mul_u32_u24_e32 v235, 0x7c2, v234
	v_lshrrev_b32_e32 v235, 16, v235
	v_mul_u32_u24_e32 v236, 33, v235
	v_sub_u32_e32 v236, v234, v236
	v_and_b32_e32 v237, 15, v236
	v_lshrrev_b32_e32 v238, 1, v237
	v_lshlrev_b32_e32 v238, 6, v238
	v_and_b32_e32 v237, 1, v237
	v_lshl_or_b32 v238, v237, 5, v238
	v_lshrrev_b32_e32 v237, 4, v236
	v_lshl_or_b32 v238, v237, 4, v238
	v_lshrrev_b32_e32 v237, 5, v235
	v_lshl_or_b32 v238, v237, 11, v238
	v_and_b32_e32 v237, 31, v235
	v_mul_u32_u24_e32 v237, 0x3800, v237
	v_add_u32_e32 v233, v237, v238
	s_add_u32 s98, s100, s70
	s_addc_u32 s99, s101, s71
	s_lshl_b32 m0, s55, 10
	s_nop 0
	global_load_lds_dwordx4 v229, s[98:99]
	s_add_u32 m0, m0, 0x2000
	s_nop 0
	global_load_lds_dwordx4 v230, s[98:99]
	s_add_u32 m0, m0, 0x2000
	s_nop 0
	global_load_lds_dwordx4 v231, s[98:99]
	s_add_u32 m0, m0, 0x2000
	s_nop 0
	global_load_lds_dwordx4 v232, s[98:99]
	s_cmp_lg_u32 s55, 0
	s_cbranch_scc1 .Ldma_skip_pro
	s_mov_b32 m0, 0x8000
	s_nop 0
	global_load_lds_dwordx4 v233, s[98:99]

; #define LAS __attribute__((address_space(3)))
; __device__ __forceinline__ unsigned pk2(float lo, float hi) { unsigned r; asm("v_cvt_pk_bf16_f32 %0, %1, %2" : "=v"(r) : "v"(lo), "v"(hi)); return r; }
; #define MFMA16(a, b, c) __builtin_amdgcn_mfma_f32_16x16x32_bf16((a), (b), (c), 0, 0, 0)
; #define LDS_BARRIER() do { asm volatile("s_waitcnt lgkmcnt(0)" ::: "memory"); __builtin_amdgcn_s_barrier(); asm volatile("" ::: "memory"); } while (0)
; #define WRITE_CS() do { _Pragma("unroll") for (int kti = 0; kti < 2; ++kti) _Pragma("unroll") for (int vt = 0; vt < 5; ++vt) \
;         *(LAS u32x2*)(L + L_CS + (vt * 16 + lr) * 528 + ((2 * wave + kti) * 16 + g * 4) * 2) = (u32x2){pk2(Cacc[kti][vt][0], Cacc[kti][vt][1]), pk2(Cacc[kti][vt][2], Cacc[kti][vt][3])}; } while (0)
; __device__ __forceinline__ void mlstm_item(const Args& a, LAS unsigned char* L, bool sample, int b, int hh, int sl, bool dry = false) {
;     ...
;             f32x4 sM = MFMA16(Av, Bs, z4);
;             f32x4 cM = z4;
; #pragma unroll
;             for (int kk = 0; kk < 8; ++kk) cM = MFMA16(Af[kk], Bf[kk], cM);
;             const float d0 = __expf(m0c + GFM[c * 32 + t]), en = GEN[c * 32 + t];
;             const LAS float* NQ = (const LAS float*)(L + L_NQ);
;             const float nq = (NQ[t] + NQ[32 + t]) + d0 * (NQ[64 + t] + NQ[96 + t]);
;             const float inv = __builtin_amdgcn_rcpf(fmaxf(fabsf(nq), en));
;             float hv[4];
; #pragma unroll
;             for (int j = 0; j < 4; ++j) hv[j] = (sM[j] + d0 * cM[j]) * inv;
;             if (dry) *(u32x2*)((bf16_t*)a.out + (size_t)(rowbase + c * 32 + t) * 1024 + hh * 256 + sl * 64 + vt * 16 + g * 4) = (u32x2){pk2(hv[0], hv[1]), pk2(hv[2], hv[3])};
;             else *(u32x2*)(U + (size_t)(rowbase + c * 32 + t) * LDU + C_V + hh * 256 + sl * 64 + vt * 16 + g * 4) = (u32x2){pk2(hv[0], hv[1]), pk2(hv[2], hv[3])};
;         }
;         LDS_BARRIER();
;         WRITE_CS();
.LBB0_661:
	ds_read_b64_tr_b16 v[58:59], v97 offset:19008
	s_waitcnt lgkmcnt(1)
	ds_read_b64_tr_b16 v[56:57], v97 offset:16896
	ds_read_b64_tr_b16 v[116:117], v97 offset:16912
	ds_read_b64_tr_b16 v[118:119], v97 offset:19024
	ds_read_b128 v[120:123], v95 offset:40192
	ds_read_b128 v[124:127], v95 offset:41472
	ds_read_b128 v[128:131], v95 offset:42752
	ds_read_b128 v[132:135], v95 offset:44032
	ds_read_b128 v[136:139], v95 offset:45312
	v_pk_mul_f32 v[38:39], v[38:39], v[76:77] op_sel_hi:[1,0]
	v_pk_mul_f32 v[36:37], v[36:37], v[76:77] op_sel_hi:[1,0]
	v_pk_mul_f32 v[54:55], v[54:55], v[76:77] op_sel_hi:[1,0]
	v_pk_mul_f32 v[52:53], v[52:53], v[76:77] op_sel_hi:[1,0]
	v_pk_mul_f32 v[50:51], v[50:51], v[76:77] op_sel_hi:[1,0]
	v_pk_mul_f32 v[48:49], v[48:49], v[76:77] op_sel_hi:[1,0]
	v_pk_mul_f32 v[46:47], v[46:47], v[76:77] op_sel_hi:[1,0]
	v_pk_mul_f32 v[44:45], v[44:45], v[76:77] op_sel_hi:[1,0]
	v_pk_mul_f32 v[42:43], v[42:43], v[76:77] op_sel_hi:[1,0]
	v_pk_mul_f32 v[40:41], v[40:41], v[76:77] op_sel_hi:[1,0]
	s_waitcnt lgkmcnt(4)
	v_mfma_f32_16x16x32_bf16 v[36:39], v[56:59], v[120:123], v[36:39]
	v_mul_f32_e64 v34, v34, v76
	v_mul_f32_e64 v35, v35, v76
	v_pk_mul_f32 v[32:33], v[32:33], v[76:77] op_sel_hi:[1,0]
	v_pk_mul_f32 v[30:31], v[30:31], v[76:77] op_sel_hi:[1,0]
	s_waitcnt lgkmcnt(3)
	v_mfma_f32_16x16x32_bf16 v[52:55], v[56:59], v[124:127], v[52:55]
	v_mul_f32_e64 v28, v28, v76
	v_mul_f32_e64 v29, v29, v76
	v_pk_mul_f32 v[26:27], v[26:27], v[76:77] op_sel_hi:[1,0]
	v_pk_mul_f32 v[24:25], v[24:25], v[76:77] op_sel_hi:[1,0]
	s_waitcnt lgkmcnt(2)
	v_mfma_f32_16x16x32_bf16 v[48:51], v[56:59], v[128:131], v[48:51]
	v_mul_f32_e64 v22, v22, v76
	v_mul_f32_e64 v23, v23, v76
	v_pk_mul_f32 v[20:21], v[20:21], v[76:77] op_sel_hi:[1,0]
	v_pk_mul_f32 v[18:19], v[18:19], v[76:77] op_sel_hi:[1,0]
	s_waitcnt lgkmcnt(1)
	v_mfma_f32_16x16x32_bf16 v[44:47], v[56:59], v[132:135], v[44:47]
	v_mul_f32_e64 v16, v16, v76
	v_mul_f32_e64 v17, v17, v76
	s_waitcnt lgkmcnt(0)
	s_barrier
	s_waitcnt lgkmcnt(0)
	v_mfma_f32_16x16x32_bf16 v[40:43], v[56:59], v[136:139], v[40:43]
	v_add_u32_e32 v58, v70, v99
	v_add_u32_e32 v57, v104, v222
	v_mfma_f32_16x16x32_bf16 v[32:35], v[116:119], v[120:123], v[32:35]
	v_mfma_f32_16x16x32_bf16 v[28:31], v[116:119], v[124:127], v[28:31]
	v_mfma_f32_16x16x32_bf16 v[24:27], v[116:119], v[128:131], v[24:27]
	v_mfma_f32_16x16x32_bf16 v[20:23], v[116:119], v[132:135], v[20:23]
	v_mfma_f32_16x16x32_bf16 v[16:19], v[116:119], v[136:139], v[16:19]
	ds_read_b128 v[116:119], v91 offset:46592
	ds_read_b128 v[120:123], v58 offset:33792
	ds_read_b128 v[124:127], v90 offset:49152
	ds_read_b128 v[128:131], v57
	ds_read_b128 v[132:135], v90 offset:49184
	ds_read_b128 v[136:139], v57 offset:32
	ds_read_b128 v[140:143], v90 offset:49216
	ds_read_b128 v[144:147], v57 offset:64
	ds_read_b128 v[148:151], v90 offset:49248
	ds_read_b128 v[152:155], v57 offset:96
	ds_read_b128 v[156:159], v90 offset:49280
	ds_read_b128 v[160:163], v57 offset:128
	ds_read_b128 v[164:167], v90 offset:49312
	ds_read_b128 v[168:171], v57 offset:160
	ds_read_b128 v[172:175], v90 offset:49344
	ds_read_b128 v[176:179], v57 offset:192
	ds_read_b128 v[182:185], v90 offset:49376
	ds_read_b128 v[186:189], v57 offset:224
	s_waitcnt lgkmcnt(14)
	v_mfma_f32_16x16x32_bf16 v[124:127], v[124:127], v[128:131], 0
	v_add_u32_e32 v56, 0, v110
	v_add_u32_e32 v59, 0x16500, v56
	ds_read_b32 v59, v59
	s_waitcnt lgkmcnt(13)
	v_mfma_f32_16x16x32_bf16 v[124:127], v[132:135], v[136:139], v[124:127]
	v_add_u32_e32 v56, 0x1a500, v56
	ds_read2_b32 v[128:129], v89 offset1:32
	ds_read_b32 v56, v56
	ds_read2_b32 v[130:131], v89 offset0:64 offset1:96
	s_waitcnt lgkmcnt(14)
	v_mfma_f32_16x16x32_bf16 v[124:127], v[140:143], v[144:147], v[124:127]
	s_waitcnt lgkmcnt(3)
	v_add_f32_e32 v59, v115, v59
	v_mul_f32_e32 v59, 0x3fb8aa3b, v59
	v_exp_f32_e32 v59, v59
	v_mfma_f32_16x16x32_bf16 v[124:127], v[148:151], v[152:155], v[124:127]
	s_waitcnt lgkmcnt(2)
	v_mov_b32_e32 v132, v128
	s_waitcnt lgkmcnt(0)
	v_mov_b32_e32 v133, v130
	v_mov_b32_e32 v130, v129
	v_mfma_f32_16x16x32_bf16 v[124:127], v[156:159], v[160:163], v[124:127]
	v_add_f32_e64 v128, v132, v130
	v_add_f32_e64 v129, v133, v131
	v_max_f32_e32 v56, v56, v56
	v_fmac_f32_e32 v128, v59, v129
	v_mfma_f32_16x16x32_bf16 v[124:127], v[164:167], v[168:171], v[124:127]
	v_max_f32_e64 v56, |v128|, v56
	v_rcp_f32_e32 v56, v56
	s_lshl_b32 s42, s53, 1
	v_mfma_f32_16x16x32_bf16 v[124:127], v[172:175], v[176:179], v[124:127]
	s_mov_b32 s59, s43
	s_add_i32 s16, s16, 4
	s_add_u32 s70, s70, 0x70000
	v_mfma_f32_16x16x32_bf16 v[124:127], v[182:185], v[186:189], v[124:127]
	s_addc_u32 s71, s71, 0
	v_add_u32_e32 v114, 0x80, v114
	v_add_u32_e32 v110, 0x80, v110
	v_mfma_f32_16x16x32_bf16 v[116:119], v[120:123], v[116:119], 0
	v_cvt_pk_bf16_f32 v120, v48, v49
	v_cvt_pk_bf16_f32 v121, v50, v51
	s_cmp_eq_u32 s70, 0x1b90000
	v_add_u32_e32 v111, 0x80, v111
	v_cvt_pk_bf16_f32 v122, v44, v45
	s_nop 5
	v_fma_f32 v76, v124, v59, v116
	v_fma_f32 v115, v125, v59, v117
	v_fma_f32 v116, v126, v59, v118
	v_fmac_f32_e32 v119, v127, v59
	v_mul_f32_e32 v76, v76, v56
	v_mul_f32_e32 v115, v115, v56
	v_mul_f32_e32 v117, v116, v56
	v_mul_f32_e32 v56, v119, v56
	v_mov_b64_e32 v[118:119], s[28:29]
	v_mad_i64_i32 v[118:119], s[72:73], v109, s84, v[118:119]
	v_lshl_add_u64 v[118:119], v[118:119], 0, s[42:43]
	v_lshl_add_u64 v[118:119], v[118:119], 0, s[58:59]
	v_lshl_add_u64 v[118:119], s[56:57], 1, v[118:119]
	v_lshl_add_u64 v[118:119], v[118:119], 0, v[60:61]
	v_add_co_u32_e32 v118, vcc, s85, v118
	v_cvt_pk_bf16_f32 v116, v76, v115
	v_cvt_pk_bf16_f32 v117, v117, v56
	v_add_u32_e32 v59, 0xc000, v113
	s_nop 0
	v_addc_co_u32_e32 v119, vcc, 0, v119, vcc
	global_store_dwordx2 v[118:119], v[116:117], off
	v_cvt_pk_bf16_f32 v116, v36, v37
	v_cvt_pk_bf16_f32 v117, v38, v39
	s_waitcnt lgkmcnt(0)
	s_barrier
	s_add_u32 s98, s100, s70
	s_addc_u32 s99, s101, s71
	s_lshl_b32 m0, s55, 10
	s_nop 0
	global_load_lds_dwordx4 v229, s[98:99]
	s_add_u32 m0, m0, 0x2000
	s_nop 0
	global_load_lds_dwordx4 v230, s[98:99]
	s_add_u32 m0, m0, 0x2000
	s_nop 0
	global_load_lds_dwordx4 v231, s[98:99]
	s_add_u32 m0, m0, 0x2000
	s_nop 0
	global_load_lds_dwordx4 v232, s[98:99]
	s_cmp_lg_u32 s55, 0
	s_cbranch_scc1 .Ldma_skip_loop
	s_mov_b32 m0, 0x8000
	s_nop 0
	global_load_lds_dwordx4 v233, s[98:99]
; #define LAS __attribute__((address_space(3)))
; __device__ __forceinline__ float bf2f(unsigned b) { return __uint_as_float(b << 16); }
; __device__ __forceinline__ unsigned pk2(float lo, float hi) { unsigned r; asm("v_cvt_pk_bf16_f32 %0, %1, %2" : "=v"(r) : "v"(lo), "v"(hi)); return r; }
; #define LDS_BARRIER() do { asm volatile("s_waitcnt lgkmcnt(0)" ::: "memory"); __builtin_amdgcn_s_barrier(); asm volatile("" ::: "memory"); } while (0)
; #define WRITE_CS() do { _Pragma("unroll") for (int kti = 0; kti < 2; ++kti) _Pragma("unroll") for (int vt = 0; vt < 5; ++vt) \
;         *(LAS u32x2*)(L + L_CS + (vt * 16 + lr) * 528 + ((2 * wave + kti) * 16 + g * 4) * 2) = (u32x2){pk2(Cacc[kti][vt][0], Cacc[kti][vt][1]), pk2(Cacc[kti][vt][2], Cacc[kti][vt][3])}; } while (0)
; __device__ __forceinline__ void mlstm_item(const Args& a, LAS unsigned char* L, bool sample, int b, int hh, int sl, bool dry = false) {
;     ...
;     for (int c = 0; c < nchunks; ++c) {
; #pragma unroll
;         for (int i = 0; i < 2; ++i) { *(LAS u32x4*)(L + L_QS + (prow + 16 * i) * 528 + pcc * 16) = qreg[i]; *(LAS u32x4*)(L + L_KS + (prow + 16 * i) * 528 + pcc * 16) = kreg[i]; }
;         if (tid < 256) {
;             const float wL0 = GWL[c * 32 + 2 * sp], wL1 = GWL[c * 32 + 2 * sp + 1];
;             const unsigned r0w[2] = {vreg0.x, vreg0.y}, r1w[2] = {vreg1.x, vreg1.y};
; #pragma unroll
;             for (int i = 0; i < 4; ++i) { const unsigned e0 = (i & 1) ? (r0w[i >> 1] >> 16) : (r0w[i >> 1] & 0xffffu), e1 = (i & 1) ? (r1w[i >> 1] >> 16) : (r1w[i >> 1] & 0xffffu);
;                 *(LAS unsigned*)(L + L_VT + (vq * 4 + i) * 80 + sp * 4) = e0 | (e1 << 16);
;                 *(LAS unsigned*)(L + L_VTW + (vq * 4 + i) * 80 + sp * 4) = pk2(bf2f(e0) * wL0, bf2f(e1) * wL1); }
;             if (tid < 16) *(LAS unsigned*)(L + L_VTW + 64 * 80 + sp * 4) = pk2(wL0, wL1);
;         }
;         if (c + 1 < nchunks) PREFETCH(c + 1);
;     ...
;         LDS_BARRIER();
;         WRITE_CS();
.Ldma_skip_loop:
	v_cvt_pk_bf16_f32 v126, v32, v33
	v_cvt_pk_bf16_f32 v127, v34, v35
	ds_write2_b64 v59, v[116:117], v[126:127] offset1:2
	v_cvt_pk_bf16_f32 v116, v28, v29
	v_cvt_pk_bf16_f32 v117, v30, v31
	v_add_u32_e32 v76, 0xe000, v113
	v_cvt_pk_bf16_f32 v118, v52, v53
	v_cvt_pk_bf16_f32 v119, v54, v55
	ds_write2_b64 v76, v[118:119], v[116:117] offset0:32 offset1:34
	v_cvt_pk_bf16_f32 v116, v24, v25
	v_cvt_pk_bf16_f32 v117, v26, v27
	ds_write2_b64 v85, v[120:121], v[116:117] offset1:2
	v_cvt_pk_bf16_f32 v116, v20, v21
	v_cvt_pk_bf16_f32 v117, v22, v23
	v_add_u32_e32 v115, 0xe000, v86
	v_add_u32_e32 v109, 32, v109
	v_cvt_pk_bf16_f32 v123, v46, v47
	v_cvt_pk_bf16_f32 v124, v40, v41
	v_cvt_pk_bf16_f32 v125, v42, v43
	ds_write2_b64 v115, v[122:123], v[116:117] offset0:32 offset1:34
	v_cvt_pk_bf16_f32 v116, v16, v17
	v_cvt_pk_bf16_f32 v117, v18, v19
	ds_write2_b64 v67, v[124:125], v[116:117] offset0:32 offset1:34
	s_cmp_eq_u32 s70, 0x1b90000
	s_cbranch_scc1 .LBB0_676
.LBB0_662:
	s_waitcnt vmcnt(0)
	s_and_saveexec_b64 s[72:73], s[0:1]
	s_cbranch_execz .LBB0_665
	v_add_u32_e32 v0, 0, v114
	v_add_u32_e32 v0, 0x1c500, v0
	ds_read_b64 v[0:1], v0
	v_lshlrev_b32_e32 v2, 16, v64
	v_lshlrev_b32_e32 v4, 16, v62
	v_and_or_b32 v5, v62, s88, v2
	v_add_u32_e32 v3, v106, v108
	s_waitcnt lgkmcnt(0)
	v_mul_f32_e32 v4, v0, v4
	v_mul_f32_e32 v2, v1, v2
	v_cvt_pk_bf16_f32 v2, v4, v2
	v_and_b32_e32 v4, 0xffff0000, v64
	v_or_b32_sdwa v6, v4, v62 dst_sel:DWORD dst_unused:UNUSED_PAD src0_sel:DWORD src1_sel:WORD_1
	v_add_u32_e32 v7, 0x8400, v3
	ds_write2_b32 v7, v5, v6 offset1:20
	v_and_b32_e32 v5, 0xffff0000, v62
	v_mul_f32_e32 v5, v0, v5
	v_mul_f32_e32 v4, v1, v4
	v_add_u32_e32 v3, 0x9c00, v3
	v_cvt_pk_bf16_f32 v4, v5, v4
	ds_write2_b32 v3, v2, v4 offset0:64 offset1:84
	v_lshlrev_b32_e32 v2, 16, v65
	v_lshlrev_b32_e32 v5, 16, v63
	v_and_or_b32 v4, v63, s88, v2
	v_mul_f32_e32 v5, v0, v5
	v_mul_f32_e32 v2, v1, v2
	v_cvt_pk_bf16_f32 v2, v5, v2
	v_and_b32_e32 v5, 0xffff0000, v65
	v_or_b32_sdwa v6, v5, v63 dst_sel:DWORD dst_unused:UNUSED_PAD src0_sel:DWORD src1_sel:WORD_1
	ds_write2_b32 v7, v4, v6 offset0:40 offset1:60
	v_and_b32_e32 v4, 0xffff0000, v63
	v_mul_f32_e32 v4, v0, v4
	v_mul_f32_e32 v5, v1, v5
	v_cvt_pk_bf16_f32 v4, v4, v5
	ds_write2_b32 v3, v2, v4 offset0:104 offset1:124
	s_and_b64 exec, exec, s[14:15]
	s_cbranch_execz .LBB0_665
	v_cvt_pk_bf16_f32 v0, v0, v1
	ds_write_b32 v106, v0 offset:45312

; #define LAS __attribute__((address_space(3)))
; __device__ __forceinline__ float bf2f(unsigned b) { return __uint_as_float(b << 16); }
; __device__ __forceinline__ unsigned pk2(float lo, float hi) { unsigned r; asm("v_cvt_pk_bf16_f32 %0, %1, %2" : "=v"(r) : "v"(lo), "v"(hi)); return r; }
; __device__ __forceinline__ void mlstm_item(const Args& a, LAS unsigned char* L, bool sample, int b, int hh, int sl, bool dry = false) {
;     ...
;     for (int c = 0; c < nchunks; ++c) {
; #pragma unroll
;         for (int i = 0; i < 2; ++i) { *(LAS u32x4*)(L + L_QS + (prow + 16 * i) * 528 + pcc * 16) = qreg[i]; *(LAS u32x4*)(L + L_KS + (prow + 16 * i) * 528 + pcc * 16) = kreg[i]; }
;         if (tid < 256) {
;             const float wL0 = GWL[c * 32 + 2 * sp], wL1 = GWL[c * 32 + 2 * sp + 1];
;             const unsigned r0w[2] = {vreg0.x, vreg0.y}, r1w[2] = {vreg1.x, vreg1.y};
; #pragma unroll
;             for (int i = 0; i < 4; ++i) { const unsigned e0 = (i & 1) ? (r0w[i >> 1] >> 16) : (r0w[i >> 1] & 0xffffu), e1 = (i & 1) ? (r1w[i >> 1] >> 16) : (r1w[i >> 1] & 0xffffu);
;                 *(LAS unsigned*)(L + L_VT + (vq * 4 + i) * 80 + sp * 4) = e0 | (e1 << 16);
;                 *(LAS unsigned*)(L + L_VTW + (vq * 4 + i) * 80 + sp * 4) = pk2(bf2f(e0) * wL0, bf2f(e1) * wL1); }
;             if (tid < 16) *(LAS unsigned*)(L + L_VTW + 64 * 80 + sp * 4) = pk2(wL0, wL1);
;         }
.LBB0_676:
	s_waitcnt vmcnt(0)
	s_and_saveexec_b64 s[70:71], s[0:1]
	s_cbranch_execz .LBB0_679
	s_add_i32 s0, 0, 0x1c500
	v_add_u32_e32 v0, s0, v107
	ds_read_b64 v[0:1], v0 offset:8064
	v_lshlrev_b32_e32 v2, 16, v64
	v_lshlrev_b32_e32 v4, 16, v62
	v_and_or_b32 v5, v62, s88, v2
	v_add_u32_e32 v3, v106, v108
	s_waitcnt lgkmcnt(0)
	v_mul_f32_e32 v4, v0, v4
	v_mul_f32_e32 v2, v1, v2
	v_cvt_pk_bf16_f32 v2, v4, v2
	v_and_b32_e32 v4, 0xffff0000, v64
	v_or_b32_sdwa v6, v4, v62 dst_sel:DWORD dst_unused:UNUSED_PAD src0_sel:DWORD src1_sel:WORD_1
	v_add_u32_e32 v7, 0x8400, v3
	ds_write2_b32 v7, v5, v6 offset1:20
	v_and_b32_e32 v5, 0xffff0000, v62
	v_mul_f32_e32 v5, v0, v5
	v_mul_f32_e32 v4, v1, v4
	v_add_u32_e32 v3, 0x9c00, v3
	v_cvt_pk_bf16_f32 v4, v5, v4
	ds_write2_b32 v3, v2, v4 offset0:64 offset1:84
	v_lshlrev_b32_e32 v2, 16, v65
	v_lshlrev_b32_e32 v5, 16, v63
	v_and_or_b32 v4, v63, s88, v2
	v_mul_f32_e32 v5, v0, v5
	v_mul_f32_e32 v2, v1, v2
	v_cvt_pk_bf16_f32 v2, v5, v2
	v_and_b32_e32 v5, 0xffff0000, v65
	v_or_b32_sdwa v6, v5, v63 dst_sel:DWORD dst_unused:UNUSED_PAD src0_sel:DWORD src1_sel:WORD_1
	ds_write2_b32 v7, v4, v6 offset0:40 offset1:60
	v_and_b32_e32 v4, 0xffff0000, v63
	v_mul_f32_e32 v4, v0, v4
	v_mul_f32_e32 v5, v1, v5
	v_cvt_pk_bf16_f32 v4, v4, v5
	ds_write2_b32 v3, v2, v4 offset0:104 offset1:124
	s_and_b64 exec, exec, s[14:15]
	s_cbranch_execz .LBB0_679
	v_cvt_pk_bf16_f32 v0, v0, v1
	ds_write_b32 v106, v0 offset:45312
